# strategy: wait at first consumer - the next attention block's norm-bound loads are waited (and the bound computed) after the bias-fill loads have been issued
# baseline (speedup 1.0000x reference)
; #define GRAB(dst) do { if (tid == 0) *nl = (int)__hip_atomic_fetch_add(qctr, 1u, __ATOMIC_RELAXED, __HIP_MEMORY_SCOPE_AGENT); __syncthreads(); dst = __builtin_amdgcn_readfirstlane(*nl); __syncthreads(); } while (0)
; __global__ void __launch_bounds__(512, 2) fox_fwd(Args args) {
;     ...
;             auto mkref = [&](int n) { const int bh = n & 31, qb = 31 - (n >> 5), b = bh >> 3, h = bh & 7;
;                 fox::BlockRef r; r.K = Kb + (size_t)bh * SEQ * HD; r.O = MIX + ((size_t)b * SEQ + (size_t)qb * 256) * DM + h * HD; r.C = Cp + (size_t)bh * SEQ; r.P0 = qb * 256;
;                 r.nrm = 1.02f * fox::SCALE * sqrtf(QN[bh * 32 + qb] * KN[bh]); return r; };
;     ...
;             int n; GRAB(n);
;             if (n < NB * NH * 32) {
;                 fox::BlockRef cur = mkref(n);
;                 fox::prime(cur, (char*)lds, S);
;                 for (;;) {
;                     int nn; GRAB(nn); const bool last = nn >= NB * NH * 32;
;                     const fox::BlockRef nxt = last ? cur : mkref(nn);
.LBB0_1120:
	s_or_b64 exec, exec, s[6:7]
	v_mov_b32_e32 v0, s0
	s_waitcnt lgkmcnt(0)
	s_barrier
	ds_read_b32 v0, v0
	s_mov_b64 s[36:37], s[18:19]
	s_mov_b64 s[38:39], s[20:21]
	s_mov_b64 s[40:41], s[22:23]
	s_mov_b32 s42, s56
	s_waitcnt lgkmcnt(0)
	v_readfirstlane_b32 s6, v0
	s_cmpk_lt_i32 s6, 0x400
	s_cselect_b64 s[34:35], -1, 0
	s_cmpk_gt_i32 s6, 0x3ff
	s_cselect_b64 s[30:31], -1, 0
	s_and_b64 vcc, exec, s[30:31]
	v_mov_b32_e32 v173, v172
	s_barrier
	s_cbranch_vccnz .LBB0_1122
	s_and_b32 s43, s6, 31
	s_ashr_i32 s7, s6, 5
	s_sub_i32 s8, 31, s7
	s_lshl_b32 s7, s43, 21
	s_add_u32 s36, s1, s7
	s_mov_b32 s9, s57
	s_addc_u32 s37, s3, 0
	s_lshl_b64 s[38:39], s[8:9], 20
	s_add_u32 s7, s25, s38
	s_addc_u32 s9, s27, s39
	s_lshl_b32 s38, s6, 22
	s_and_b32 s38, s38, 0x6000000
	s_add_u32 s7, s7, s38
	s_addc_u32 s9, s9, 0
	s_lshl_b32 s6, s6, 8
	s_and_b32 s6, s6, 0x700
	s_add_u32 s38, s7, s6
	s_addc_u32 s39, s9, 0
	s_lshl_b32 s6, s43, 15
	s_add_u32 s40, s33, s6
	s_addc_u32 s41, s46, 0
	s_lshl_b32 s6, s43, 5
	s_add_i32 s6, s6, s8
	s_mov_b32 s7, s57
	s_lshl_b32 s42, s8, 8
	s_lshl_b64 s[6:7], s[6:7], 2
	s_add_u32 s6, s47, s6
	s_addc_u32 s7, s50, s7
	s_lshl_b32 s8, s43, 2
	v_mov_b32_e32 v0, s8
	global_load_dword v9, v161, s[6:7]
	s_nop 0
	global_load_dword v8, v0, s[16:17]

; __device__ __forceinline__ void block(const BlockRef& cur, const BlockRef& nxt, char* lds, Seam& S) {
;     ...
;     if (wid == 0) { const float lim = -(88.0f + 2.0f * cur.nrm) * INV_SCALE; const int t1 = lane + 64;
;         const bool d0 = lane < NTC && bias[64 * lane + 63] < lim, d1 = t1 < NTC && bias[64 * t1 + 63] < lim;
;         int cnt = __popcll(__ballot(d0)) + __popcll(__ballot(d1)); cnt &= ~1; if (cnt > NTC - 4) cnt = NTC - 4;
;         if (lane == 0) *jl = cnt; }
; __global__ void __launch_bounds__(512, 2) fox_fwd(Args args) {
;     ...
;                 r.nrm = 1.02f * fox::SCALE * sqrtf(QN[bh * 32 + qb] * KN[bh]); return r; };
.Lbf_done:
.LBB0_1125:
	s_or_b64 exec, exec, s[6:7]
	s_and_b64 vcc, exec, s[30:31]
	s_cbranch_vccnz .Lmk_skip
	s_waitcnt vmcnt(0)
	v_mul_f32_e32 v0, v9, v8
	v_mul_f32_e32 v1, 0x4f800000, v0
	v_cmp_gt_f32_e32 vcc, s60, v0
	s_nop 1
	v_cndmask_b32_e32 v0, v0, v1, vcc
	v_sqrt_f32_e32 v1, v0
	s_nop 0
	v_add_u32_e32 v2, -1, v1
	v_add_u32_e32 v3, 1, v1
	v_fma_f32 v4, -v2, v1, v0
	v_fma_f32 v5, -v3, v1, v0
	v_cmp_ge_f32_e64 s[6:7], 0, v4
	s_nop 1
	v_cndmask_b32_e64 v1, v1, v2, s[6:7]
	v_cmp_lt_f32_e64 s[6:7], 0, v5
	s_nop 1
	v_cndmask_b32_e64 v1, v1, v3, s[6:7]
	v_mul_f32_e32 v2, 0x37800000, v1
	v_cndmask_b32_e32 v1, v1, v2, vcc
	v_cmp_class_f32_e32 vcc, v0, v168
	s_nop 1
	v_cndmask_b32_e32 v0, v1, v0, vcc
	v_mul_f32_e32 v173, 0x3db8a3c4, v0
.Lmk_skip:
	s_lshr_b32 s58, s43, 6
	v_and_b32_e32 v175, 63, v174
	s_cmp_lt_u32 s66, 64
	s_waitcnt lgkmcnt(0)
	s_barrier
	s_cbranch_scc0 .LBB0_1133
	v_fmaak_f32 v0, 2.0, v172, 0x42380000
	v_mul_f32_e32 v0, 0xc13504f3, v0
	v_cmp_gt_u32_e32 vcc, s58, v175
	s_mov_b64 s[6:7], 0
	s_mov_b64 s[8:9], 0
	s_and_saveexec_b64 s[44:45], vcc
	s_cbranch_execz .LBB0_1128
	v_lshl_add_u32 v1, v175, 8, s63
	ds_read_b32 v1, v1 offset:252
	s_waitcnt lgkmcnt(0)
	v_cmp_lt_f32_e32 vcc, v1, v0
	s_and_b64 s[8:9], vcc, exec
